# adds: FFN-up conv taps staged through free LDS by LDS-DMA at the unit-loop header and read back with ds_read_b128 in the epilogue (no vmcnt(0) drain of the LDS-DMA ring per unit)
# baseline (speedup 1.0000x reference)
;     __host__ __device__ bool next(int i, Unit& u) const { const bool ok = StaticOrder::next(i, u); u.pm = 0; u.pn = 0; return ok; }
;     __device__ __forceinline__ void operator()(const f32x4 (&acc)[2][2][4][2], const Unit& u, int wr, int wc, int fr, int fq) const {
;     ...
;         f32x4 wa2[2][3], wb2[2][3];
; #pragma unroll
;         for (int n = 0; n < 2; ++n)
; #pragma unroll
;             for (int t = 0; t < 3; ++t) { wa2[n][t] = *(const f32x4*)(cw + t * 11008 + jg0 + 4 * n); wb2[n][t] = *(const f32x4*)(cw + t * 11008 + 5504 + jg0 + 4 * n); }
;         asm volatile("" :: "v"(wa2[0][0]), "v"(wa2[0][1]), "v"(wa2[0][2]), "v"(wb2[0][0]), "v"(wb2[0][1]), "v"(wb2[0][2]), "v"(wa2[1][0]), "v"(wa2[1][1]), "v"(wa2[1][2]), "v"(wb2[1][0]), "v"(wb2[1][1]), "v"(wb2[1][2]));
; template <class Epi, class Sched, bool ALIGN_EPI = false, bool SP2 = false>
; __device__ __forceinline__ void gemm_phase(PG8_LAS unsigned char* lds, const Gemm g, const Sched& S, const Epi& E, const int wave_in) {
;     ...
;     for (;;) {
;         const bool has_next = S.next(ui + 1, nxt);
;         const char* nA = has_next ? (const char*)g.A + (size_t)nxt.pm * tstepA : cA; const char* nB = has_next ? (const char*)g.Bt + (size_t)nxt.pn * tstepB : cB;
;         for (int t = 0; t < nt; t += 2) {
;             const bool last = (t == nt - 2);
;             const char* a1 = cA + (size_t)(t + 1) * kstep;
;             const char* a2 = last ? nA : cA + (size_t)(t + 2) * kstep; const char* b2 = last ? nB : cB + (size_t)(t + 2) * kstep;
;             const char* a3 = a2 + kstep; const char* b3 = b2 + kstep;
;             if (last && has_next) S.a_ready(nxt);
.LBB0_478:
	s_ashr_i32 s41, s40, 31
	s_lshl_b64 s[42:43], s[40:41], 20
	s_add_u32 s42, s52, s42
	s_addc_u32 s43, s53, s43
	s_and_b64 s[44:45], s[10:11], exec
	s_cselect_b32 s1, s43, s47
	s_cselect_b32 s13, s42, s46
	s_ashr_i32 s39, s38, 31
	s_lshl_b64 s[44:45], s[38:39], 20
	s_add_u32 s44, s54, s44
	s_addc_u32 s45, s55, s45
	s_and_b64 s[50:51], s[10:11], exec
	s_cselect_b32 s39, s45, s49
	s_cselect_b32 s41, s44, s48
	s_add_u32 s46, s46, 0x80080
	s_addc_u32 s47, s47, 0
	s_add_u32 s72, s48, 0x100
	v_mov_b32_e32 v0, 0
	s_addc_u32 s73, s49, 0
	s_mov_b32 s74, -2
	v_mov_b32_e32 v1, v0
	v_mov_b32_e32 v2, v0
	v_mov_b32_e32 v3, v0
	v_mov_b32_e32 v4, v0
	v_mov_b32_e32 v5, v0
	v_mov_b32_e32 v6, v0
	v_mov_b32_e32 v7, v0
	v_mov_b32_e32 v16, v0
	v_mov_b32_e32 v17, v0
	v_mov_b32_e32 v18, v0
	v_mov_b32_e32 v19, v0
	v_mov_b32_e32 v24, v0
	v_mov_b32_e32 v25, v0
	v_mov_b32_e32 v26, v0
	v_mov_b32_e32 v27, v0
	v_mov_b32_e32 v32, v0
	v_mov_b32_e32 v33, v0
	v_mov_b32_e32 v34, v0
	v_mov_b32_e32 v35, v0
	v_mov_b32_e32 v40, v0
	v_mov_b32_e32 v41, v0
	v_mov_b32_e32 v42, v0
	v_mov_b32_e32 v43, v0
	v_mov_b32_e32 v72, v0
	v_mov_b32_e32 v73, v0
	v_mov_b32_e32 v74, v0
	v_mov_b32_e32 v75, v0
	v_mov_b32_e32 v104, v0
	v_mov_b32_e32 v105, v0
	v_mov_b32_e32 v106, v0
	v_mov_b32_e32 v107, v0
	v_mov_b32_e32 v8, v0
	v_mov_b32_e32 v9, v0
	v_mov_b32_e32 v10, v0
	v_mov_b32_e32 v11, v0
	v_mov_b32_e32 v12, v0
	v_mov_b32_e32 v13, v0
	v_mov_b32_e32 v14, v0
	v_mov_b32_e32 v15, v0
	v_mov_b32_e32 v20, v0
	v_mov_b32_e32 v21, v0
	v_mov_b32_e32 v22, v0
	v_mov_b32_e32 v23, v0
	v_mov_b32_e32 v28, v0
	v_mov_b32_e32 v29, v0
	v_mov_b32_e32 v30, v0
	v_mov_b32_e32 v31, v0
	v_mov_b32_e32 v36, v0
	v_mov_b32_e32 v37, v0
	v_mov_b32_e32 v38, v0
	v_mov_b32_e32 v39, v0
	v_mov_b32_e32 v68, v0
	v_mov_b32_e32 v69, v0
	v_mov_b32_e32 v70, v0
	v_mov_b32_e32 v71, v0
	v_mov_b32_e32 v76, v0
	v_mov_b32_e32 v77, v0
	v_mov_b32_e32 v78, v0
	v_mov_b32_e32 v79, v0
	v_mov_b32_e32 v108, v0
	v_mov_b32_e32 v109, v0
	v_mov_b32_e32 v110, v0
	v_mov_b32_e32 v111, v0
	v_mov_b32_e32 v112, v0
	v_mov_b32_e32 v113, v0
	v_mov_b32_e32 v114, v0
	v_mov_b32_e32 v115, v0
	v_mov_b32_e32 v116, v0
	v_mov_b32_e32 v117, v0
	v_mov_b32_e32 v118, v0
	v_mov_b32_e32 v119, v0
	v_mov_b32_e32 v128, v0
	v_mov_b32_e32 v129, v0
	v_mov_b32_e32 v130, v0
	v_mov_b32_e32 v131, v0
	v_mov_b32_e32 v136, v0
	v_mov_b32_e32 v137, v0
	v_mov_b32_e32 v138, v0
	v_mov_b32_e32 v139, v0
	v_mov_b32_e32 v144, v0
	v_mov_b32_e32 v145, v0
	v_mov_b32_e32 v146, v0
	v_mov_b32_e32 v147, v0
	v_mov_b32_e32 v152, v0
	v_mov_b32_e32 v153, v0
	v_mov_b32_e32 v154, v0
	v_mov_b32_e32 v155, v0
	v_mov_b32_e32 v160, v0
	v_mov_b32_e32 v161, v0
	v_mov_b32_e32 v162, v0
	v_mov_b32_e32 v163, v0
	v_mov_b32_e32 v168, v0
	v_mov_b32_e32 v169, v0
	v_mov_b32_e32 v170, v0
	v_mov_b32_e32 v171, v0
	v_mov_b32_e32 v120, v0
	v_mov_b32_e32 v121, v0
	v_mov_b32_e32 v122, v0
	v_mov_b32_e32 v123, v0
	v_mov_b32_e32 v124, v0
	v_mov_b32_e32 v125, v0
	v_mov_b32_e32 v126, v0
	v_mov_b32_e32 v127, v0
	v_mov_b32_e32 v132, v0
	v_mov_b32_e32 v133, v0
	v_mov_b32_e32 v134, v0
	v_mov_b32_e32 v135, v0
	v_mov_b32_e32 v140, v0
	v_mov_b32_e32 v141, v0
	v_mov_b32_e32 v142, v0
	v_mov_b32_e32 v143, v0
	v_mov_b32_e32 v148, v0
	v_mov_b32_e32 v149, v0
	v_mov_b32_e32 v150, v0
	v_mov_b32_e32 v151, v0
	v_mov_b32_e32 v156, v0
	v_mov_b32_e32 v157, v0
	v_mov_b32_e32 v158, v0
	v_mov_b32_e32 v159, v0
	v_mov_b32_e32 v164, v0
	v_mov_b32_e32 v165, v0
	v_mov_b32_e32 v166, v0
	v_mov_b32_e32 v167, v0
	v_mov_b32_e32 v172, v0
	v_mov_b32_e32 v173, v0
	v_mov_b32_e32 v174, v0
	v_mov_b32_e32 v175, v0
	s_and_b32 s99, s61, 1
	s_lshl_b32 s99, s99, 12
	s_add_u32 s99, s99, 0x20000
	s_and_b32 s98, s33, 3
	s_lshl_b32 s98, s98, 10
	s_add_u32 s98, s98, s99
	v_lshl_add_u32 v80, s0, 7, v190
	v_ashrrev_i32_e32 v81, 31, v80
	v_lshlrev_b64 v[80:81], 2, v[80:81]
	s_mov_b32 exec_lo, 0x10001
	s_mov_b32 exec_hi, 0x10001
	s_mov_b32 m0, s98
	v_lshl_add_u64 v[82:83], s[14:15], 0, v[80:81]
	global_load_lds_dwordx4 v[82:83], off
	global_load_lds_dwordx4 v[82:83], off offset:16
	s_add_u32 m0, s98, 32
	v_lshl_add_u64 v[82:83], s[26:27], 0, v[80:81]
	global_load_lds_dwordx4 v[82:83], off
	global_load_lds_dwordx4 v[82:83], off offset:16
	s_add_u32 m0, s98, 64
	v_lshl_add_u64 v[82:83], s[28:29], 0, v[80:81]
	global_load_lds_dwordx4 v[82:83], off
	global_load_lds_dwordx4 v[82:83], off offset:16
	s_add_u32 m0, s98, 96
	v_lshl_add_u64 v[82:83], s[30:31], 0, v[80:81]
	global_load_lds_dwordx4 v[82:83], off
	global_load_lds_dwordx4 v[82:83], off offset:16
	s_add_u32 m0, s98, 128
	v_lshl_add_u64 v[82:83], s[34:35], 0, v[80:81]
	global_load_lds_dwordx4 v[82:83], off
	global_load_lds_dwordx4 v[82:83], off offset:16
	s_add_u32 m0, s98, 160
	v_lshl_add_u64 v[82:83], s[36:37], 0, v[80:81]
	global_load_lds_dwordx4 v[82:83], off
	global_load_lds_dwordx4 v[82:83], off offset:16
	s_mov_b64 exec, -1

;     __device__ __forceinline__ void operator()(const f32x4 (&acc)[2][2][4][2], const Unit& u, int wr, int wc, int fr, int fq) const {
;         const int cc0 = wc * 32 + 8 * fq;
;         const int jg0 = u.pn * 128 + cc0;
;         f32x4 wa2[2][3], wb2[2][3];
; #pragma unroll
;         for (int n = 0; n < 2; ++n)
; #pragma unroll
;             for (int t = 0; t < 3; ++t) { wa2[n][t] = *(const f32x4*)(cw + t * 11008 + jg0 + 4 * n); wb2[n][t] = *(const f32x4*)(cw + t * 11008 + 5504 + jg0 + 4 * n); }
;         asm volatile("" :: "v"(wa2[0][0]), "v"(wa2[0][1]), "v"(wa2[0][2]), "v"(wb2[0][0]), "v"(wb2[0][1]), "v"(wb2[0][2]), "v"(wa2[1][0]), "v"(wa2[1][1]), "v"(wa2[1][2]), "v"(wb2[1][0]), "v"(wb2[1][1]), "v"(wb2[1][2]));
.LBB0_482:
	v_lshl_add_u32 v212, s0, 7, v190
	v_ashrrev_i32_e32 v213, 31, v212
	v_lshl_add_u32 v100, v190, 5, s99
	ds_read_b128 v[48:51], v100 offset:16
	ds_read_b128 v[84:87], v100
	ds_read_b128 v[44:47], v100 offset:48
	ds_read_b128 v[80:83], v100 offset:32
	ds_read_b128 v[56:59], v100 offset:80
	ds_read_b128 v[92:95], v100 offset:64
	ds_read_b128 v[52:55], v100 offset:112
	ds_read_b128 v[88:91], v100 offset:96
	ds_read_b128 v[60:63], v100 offset:144
	ds_read_b128 v[96:99], v100 offset:128
	ds_read_b128 v[64:67], v100 offset:176
	ds_read_b128 v[100:103], v100 offset:160
	v_mov_b32_dpp v176, v156 row_ror:15 row_mask:0xf bank_mask:0xf bound_ctrl:1
	v_mov_b32_dpp v177, v152 row_ror:15 row_mask:0xf bank_mask:0xf bound_ctrl:1
	s_ashr_i32 s13, s12, 31
	v_mov_b32_dpp v176, v172 row_shl:1 row_mask:0xf bank_mask:0xf
	v_mov_b32_dpp v177, v168 row_shl:1 row_mask:0xf bank_mask:0xf
	s_lshl_b64 s[46:47], s[12:13], 8
	s_add_u32 s41, s46, s62
	s_addc_u32 s39, s47, s65
	s_waitcnt lgkmcnt(0)
; __device__ __forceinline__ unsigned cvt_pk_bf16(float lo, float hi) { unsigned r; asm volatile("v_cvt_pk_bf16_f32 %0, %1, %2" : "=v"(r) : "v"(lo), "v"(hi)); return r; }
; template <int CTRL> __device__ __forceinline__ float dppmov(float x) { return __builtin_bit_cast(float, __builtin_amdgcn_mov_dpp(__builtin_bit_cast(int, x), CTRL, 0xf, 0xf, true)); }
; template <int CTRL> __device__ __forceinline__ float dppupd(float old, float x) { return __builtin_bit_cast(float, __builtin_amdgcn_update_dpp(__builtin_bit_cast(int, old), __builtin_bit_cast(int, x), CTRL, 0xf, 0xf, false)); }
;     __device__ __forceinline__ void operator()(const f32x4 (&acc)[2][2][4][2], const Unit& u, int wr, int wc, int fr, int fq) const {
;     ...
;                 for (int n = 0; n < 2; ++n) {
;                     const f32x4 (&wa)[3] = wa2[n]; const f32x4 (&wb)[3] = wb2[n];
;                     f32x4 ga;
; #pragma unroll
;                     for (int e = 0; e < 4; ++e) {
;                         const float ac = acc[ai][0][m][n][e], bc = acc[ai][1][m][n][e];
;                         const float apo = (m > 0) ? dppmov<0x121>(acc[ai][0][m > 0 ? m - 1 : 0][n][e]) : 0.f, bpo = (m > 0) ? dppmov<0x121>(acc[ai][1][m > 0 ? m - 1 : 0][n][e]) : 0.f;
;                         const float ano = (m < 3) ? dppmov<0x12F>(acc[ai][0][m < 3 ? m + 1 : 3][n][e]) : 0.f, bno = (m < 3) ? dppmov<0x12F>(acc[ai][1][m < 3 ? m + 1 : 3][n][e]) : 0.f;
;                         const float ap = dppupd<0x111>(apo, ac), bp = dppupd<0x111>(bpo, bc);
;                         const float an = dppupd<0x101>(ano, ac), bn = dppupd<0x101>(bno, bc);
;                         const float a = ap * wa[0][e] + ac * wa[1][e] + an * wa[2][e], b = bp * wb[0][e] + bc * wb[1][e] + bn * wb[2][e];
;                         ga[e] = a * __builtin_amdgcn_rcpf(1.f + __expf(-a)) * b;
;                     }
;                     gq[2 * n] = cvt_pk_bf16(ga[0], ga[1]); gq[2 * n + 1] = cvt_pk_bf16(ga[2], ga[3]);
;                 }
;                 const int sl = 16 * m + fr;
;                 const size_t row = (size_t)u.pm * BM + ai * HALF + wr * 64 + sl;
;                 if (sl != 0 && sl != 63) *(u32x4*)(G + row * 5504 + jg0) = (u32x4){gq[0], gq[1], gq[2], gq[3]};
	v_mul_f32_dpp v178, v172, v84 row_shr:1 row_mask:0xf bank_mask:0xf bound_ctrl:1
	v_fmac_f32_e32 v178, v172, v92
	v_fmac_f32_e32 v178, v96, v176
	v_mul_f32_dpp v176, v168, v80 row_shr:1 row_mask:0xf bank_mask:0xf bound_ctrl:1
	v_fmac_f32_e32 v176, v168, v88
	v_fmac_f32_e32 v176, v100, v177
	v_mul_f32_e32 v177, 0xbfb8aa3b, v178
	v_exp_f32_e32 v177, v177
	v_mul_f32_dpp v179, v173, v85 row_shr:1 row_mask:0xf bank_mask:0xf bound_ctrl:1
	v_fmac_f32_e32 v179, v173, v93
	v_mul_f32_dpp v214, v174, v86 row_shr:1 row_mask:0xf bank_mask:0xf bound_ctrl:1
	v_add_f32_e32 v177, 1.0, v177
	v_rcp_f32_e32 v177, v177
	v_fmac_f32_e32 v214, v174, v94
	v_mul_f32_dpp v215, v175, v87 row_shr:1 row_mask:0xf bank_mask:0xf bound_ctrl:1
	v_fmac_f32_e32 v215, v175, v95
	v_mul_f32_e32 v177, v178, v177
	v_mul_f32_e32 v176, v176, v177
	v_mov_b32_dpp v178, v153 row_ror:15 row_mask:0xf bank_mask:0xf bound_ctrl:1
	v_mov_b32_dpp v177, v157 row_ror:15 row_mask:0xf bank_mask:0xf bound_ctrl:1
	v_mul_f32_dpp v216, v166, v50 row_shr:1 row_mask:0xf bank_mask:0xf bound_ctrl:1
	v_mov_b32_dpp v178, v169 row_shl:1 row_mask:0xf bank_mask:0xf
	v_mov_b32_dpp v177, v173 row_shl:1 row_mask:0xf bank_mask:0xf
	v_fmac_f32_e32 v179, v97, v177
	v_fmac_f32_e32 v216, v166, v58
	v_mul_f32_dpp v177, v169, v81 row_shr:1 row_mask:0xf bank_mask:0xf bound_ctrl:1
	v_fmac_f32_e32 v177, v169, v89
	v_fmac_f32_e32 v177, v101, v178
	v_mul_f32_e32 v178, 0xbfb8aa3b, v179
	v_exp_f32_e32 v178, v178
	v_mul_f32_dpp v217, v167, v51 row_shr:1 row_mask:0xf bank_mask:0xf bound_ctrl:1
	v_fmac_f32_e32 v217, v167, v59
	v_add_f32_e32 v178, 1.0, v178
	v_rcp_f32_e32 v178, v178
	s_nop 0
	v_mul_f32_e32 v178, v179, v178
	v_mul_f32_e32 v177, v177, v178
	s_nop 0
	v_mov_b32_dpp v178, v158 row_ror:15 row_mask:0xf bank_mask:0xf bound_ctrl:1
	v_mov_b32_dpp v179, v154 row_ror:15 row_mask:0xf bank_mask:0xf bound_ctrl:1
	v_cvt_pk_bf16_f32 v176, v176, v177
	s_nop 0
	v_mov_b32_dpp v178, v174 row_shl:1 row_mask:0xf bank_mask:0xf
	v_fmac_f32_e32 v214, v98, v178
	v_mov_b32_dpp v179, v170 row_shl:1 row_mask:0xf bank_mask:0xf
	v_mul_f32_dpp v178, v170, v82 row_shr:1 row_mask:0xf bank_mask:0xf bound_ctrl:1
	v_fmac_f32_e32 v178, v170, v90
	v_fmac_f32_e32 v178, v102, v179
	v_mul_f32_e32 v179, 0xbfb8aa3b, v214
	v_exp_f32_e32 v179, v179
	s_nop 0
	v_add_f32_e32 v179, 1.0, v179
	v_rcp_f32_e32 v179, v179
	s_nop 0
	v_mul_f32_e32 v179, v214, v179
	v_mul_f32_e32 v178, v178, v179
	s_nop 0
	v_mov_b32_dpp v179, v159 row_ror:15 row_mask:0xf bank_mask:0xf bound_ctrl:1
	v_mov_b32_dpp v214, v155 row_ror:15 row_mask:0xf bank_mask:0xf bound_ctrl:1
	s_nop 0
	v_mov_b32_dpp v179, v175 row_shl:1 row_mask:0xf bank_mask:0xf
	v_fmac_f32_e32 v215, v99, v179
	v_mov_b32_dpp v214, v171 row_shl:1 row_mask:0xf bank_mask:0xf
	v_mul_f32_dpp v179, v171, v83 row_shr:1 row_mask:0xf bank_mask:0xf bound_ctrl:1
	v_fmac_f32_e32 v179, v171, v91
	v_fmac_f32_e32 v179, v103, v214
	v_mul_f32_e32 v214, 0xbfb8aa3b, v215
	v_exp_f32_e32 v214, v214
	s_nop 0
	v_add_f32_e32 v214, 1.0, v214
	v_rcp_f32_e32 v214, v214
	s_nop 0
	v_mul_f32_e32 v214, v215, v214
	v_mul_f32_e32 v179, v179, v214
	v_cvt_pk_bf16_f32 v177, v178, v179
	v_mov_b32_dpp v178, v148 row_ror:15 row_mask:0xf bank_mask:0xf bound_ctrl:1
	v_mul_f32_dpp v214, v164, v48 row_shr:1 row_mask:0xf bank_mask:0xf bound_ctrl:1
	v_fmac_f32_e32 v214, v164, v56
	v_mov_b32_dpp v178, v164 row_shl:1 row_mask:0xf bank_mask:0xf
	v_mov_b32_dpp v179, v144 row_ror:15 row_mask:0xf bank_mask:0xf bound_ctrl:1
	v_fmac_f32_e32 v214, v60, v178
	v_mul_f32_dpp v178, v160, v44 row_shr:1 row_mask:0xf bank_mask:0xf bound_ctrl:1
	v_mov_b32_dpp v179, v160 row_shl:1 row_mask:0xf bank_mask:0xf
	v_fmac_f32_e32 v178, v160, v52
	v_fmac_f32_e32 v178, v64, v179
	v_mul_f32_e32 v179, 0xbfb8aa3b, v214
	v_exp_f32_e32 v179, v179
	v_mul_f32_dpp v215, v165, v49 row_shr:1 row_mask:0xf bank_mask:0xf bound_ctrl:1
	v_fmac_f32_e32 v215, v165, v57
	v_add_f32_e32 v179, 1.0, v179
	v_rcp_f32_e32 v179, v179
	s_nop 0
	v_mul_f32_e32 v179, v214, v179
	v_mul_f32_e32 v178, v178, v179
	s_nop 0
	v_mov_b32_dpp v179, v149 row_ror:15 row_mask:0xf bank_mask:0xf bound_ctrl:1
	v_mov_b32_dpp v214, v145 row_ror:15 row_mask:0xf bank_mask:0xf bound_ctrl:1
	s_nop 0
	v_mov_b32_dpp v179, v165 row_shl:1 row_mask:0xf bank_mask:0xf
	v_fmac_f32_e32 v215, v61, v179
	v_mov_b32_dpp v214, v161 row_shl:1 row_mask:0xf bank_mask:0xf
	v_mul_f32_dpp v179, v161, v45 row_shr:1 row_mask:0xf bank_mask:0xf bound_ctrl:1
	v_fmac_f32_e32 v179, v161, v53
	v_fmac_f32_e32 v179, v65, v214
	v_mul_f32_e32 v214, 0xbfb8aa3b, v215
	v_exp_f32_e32 v214, v214
	s_nop 0
	v_add_f32_e32 v214, 1.0, v214
	v_rcp_f32_e32 v214, v214
	s_nop 0
	v_mul_f32_e32 v214, v215, v214
	v_mul_f32_e32 v179, v179, v214
	s_nop 0
	v_mov_b32_dpp v214, v150 row_ror:15 row_mask:0xf bank_mask:0xf bound_ctrl:1
	v_mov_b32_dpp v215, v146 row_ror:15 row_mask:0xf bank_mask:0xf bound_ctrl:1
	v_cvt_pk_bf16_f32 v178, v178, v179
	s_nop 0
	v_mov_b32_dpp v214, v166 row_shl:1 row_mask:0xf bank_mask:0xf
	v_fmac_f32_e32 v216, v62, v214
	v_mov_b32_dpp v215, v162 row_shl:1 row_mask:0xf bank_mask:0xf
	v_mul_f32_dpp v214, v162, v46 row_shr:1 row_mask:0xf bank_mask:0xf bound_ctrl:1
	v_fmac_f32_e32 v214, v162, v54
	v_fmac_f32_e32 v214, v66, v215
	v_mul_f32_e32 v215, 0xbfb8aa3b, v216
	v_exp_f32_e32 v215, v215
	s_nop 0
	v_add_f32_e32 v215, 1.0, v215
	v_rcp_f32_e32 v215, v215
	s_nop 0
	v_mul_f32_e32 v215, v216, v215
	v_mul_f32_e32 v214, v214, v215
	s_nop 0
	v_mov_b32_dpp v215, v151 row_ror:15 row_mask:0xf bank_mask:0xf bound_ctrl:1
	v_mov_b32_dpp v216, v147 row_ror:15 row_mask:0xf bank_mask:0xf bound_ctrl:1
	s_nop 0
	v_mov_b32_dpp v215, v167 row_shl:1 row_mask:0xf bank_mask:0xf
	v_fmac_f32_e32 v217, v63, v215
	v_mov_b32_dpp v216, v163 row_shl:1 row_mask:0xf bank_mask:0xf
	v_mul_f32_dpp v215, v163, v47 row_shr:1 row_mask:0xf bank_mask:0xf bound_ctrl:1
	v_fmac_f32_e32 v215, v163, v55
	v_fmac_f32_e32 v215, v67, v216
	v_mul_f32_e32 v216, 0xbfb8aa3b, v217
	v_exp_f32_e32 v216, v216
	s_nop 0
	v_add_f32_e32 v216, 1.0, v216
	v_rcp_f32_e32 v216, v216
	s_nop 0
	v_mul_f32_e32 v216, v217, v216
	v_mul_f32_e32 v215, v215, v216
	v_cvt_pk_bf16_f32 v179, v214, v215
	s_and_saveexec_b64 s[46:47], s[2:3]
	s_load_dword s72, s[94:95], 0xe8
	v_readlane_b32 s73, v255, 2
	s_cbranch_execz .LBB0_484
	v_or_b32_e32 v216, s41, v188
	v_mov_b64_e32 v[214:215], s[18:19]
	v_mad_u64_u32 v[214:215], s[48:49], v216, s70, v[214:215]
	v_mad_i32_i24 v215, s39, v250, v215
	v_lshl_add_u64 v[214:215], v[212:213], 1, v[214:215]
	global_store_dwordx4 v[214:215], v[176:179], off

;     __host__ __device__ bool next(int i, Unit& u) const { const bool ok = StaticOrder::next(i, u); u.pm = 0; u.pn = 0; return ok; }
;     __device__ __forceinline__ void operator()(const f32x4 (&acc)[2][2][4][2], const Unit& u, int wr, int wc, int fr, int fq) const {
;     ...
;         f32x4 wa2[2][3], wb2[2][3];
; #pragma unroll
;         for (int n = 0; n < 2; ++n)
; #pragma unroll
;             for (int t = 0; t < 3; ++t) { wa2[n][t] = *(const f32x4*)(cw + t * 11008 + jg0 + 4 * n); wb2[n][t] = *(const f32x4*)(cw + t * 11008 + 5504 + jg0 + 4 * n); }
;         asm volatile("" :: "v"(wa2[0][0]), "v"(wa2[0][1]), "v"(wa2[0][2]), "v"(wb2[0][0]), "v"(wb2[0][1]), "v"(wb2[0][2]), "v"(wa2[1][0]), "v"(wa2[1][1]), "v"(wa2[1][2]), "v"(wb2[1][0]), "v"(wb2[1][1]), "v"(wb2[1][2]));
; template <class Epi, class Sched, bool ALIGN_EPI = false, bool SP2 = false>
; __device__ __forceinline__ void gemm_phase(PG8_LAS unsigned char* lds, const Gemm g, const Sched& S, const Epi& E, const int wave_in) {
;     ...
;     for (;;) {
;         const bool has_next = S.next(ui + 1, nxt);
;         const char* nA = has_next ? (const char*)g.A + (size_t)nxt.pm * tstepA : cA; const char* nB = has_next ? (const char*)g.Bt + (size_t)nxt.pn * tstepB : cB;
;         for (int t = 0; t < nt; t += 2) {
;             const bool last = (t == nt - 2);
;             const char* a1 = cA + (size_t)(t + 1) * kstep;
;             const char* a2 = last ? nA : cA + (size_t)(t + 2) * kstep; const char* b2 = last ? nB : cB + (size_t)(t + 2) * kstep;
;             const char* a3 = a2 + kstep; const char* b3 = b2 + kstep;
;             if (last && has_next) S.a_ready(nxt);
.LBB0_1218:
	s_ashr_i32 s41, s40, 31
	s_lshl_b64 s[42:43], s[40:41], 20
	s_add_u32 s42, s52, s42
	s_addc_u32 s43, s53, s43
	s_and_b64 s[44:45], s[10:11], exec
	s_cselect_b32 s1, s43, s47
	s_cselect_b32 s13, s42, s46
	s_ashr_i32 s39, s38, 31
	s_lshl_b64 s[44:45], s[38:39], 20
	s_add_u32 s44, s54, s44
	s_addc_u32 s45, s55, s45
	s_and_b64 s[50:51], s[10:11], exec
	s_cselect_b32 s39, s45, s49
	s_cselect_b32 s41, s44, s48
	s_add_u32 s46, s46, 0x80080
	s_addc_u32 s47, s47, 0
	s_add_u32 s72, s48, 0x100
	v_mov_b32_e32 v0, 0
	s_addc_u32 s73, s49, 0
	s_mov_b32 s74, -2
	v_mov_b32_e32 v1, v0
	v_mov_b32_e32 v2, v0
	v_mov_b32_e32 v3, v0
	v_mov_b32_e32 v4, v0
	v_mov_b32_e32 v5, v0
	v_mov_b32_e32 v6, v0
	v_mov_b32_e32 v7, v0
	v_mov_b32_e32 v16, v0
	v_mov_b32_e32 v17, v0
	v_mov_b32_e32 v18, v0
	v_mov_b32_e32 v19, v0
	v_mov_b32_e32 v24, v0
	v_mov_b32_e32 v25, v0
	v_mov_b32_e32 v26, v0
	v_mov_b32_e32 v27, v0
	v_mov_b32_e32 v32, v0
	v_mov_b32_e32 v33, v0
	v_mov_b32_e32 v34, v0
	v_mov_b32_e32 v35, v0
	v_mov_b32_e32 v40, v0
	v_mov_b32_e32 v41, v0
	v_mov_b32_e32 v42, v0
	v_mov_b32_e32 v43, v0
	v_mov_b32_e32 v72, v0
	v_mov_b32_e32 v73, v0
	v_mov_b32_e32 v74, v0
	v_mov_b32_e32 v75, v0
	v_mov_b32_e32 v104, v0
	v_mov_b32_e32 v105, v0
	v_mov_b32_e32 v106, v0
	v_mov_b32_e32 v107, v0
	v_mov_b32_e32 v8, v0
	v_mov_b32_e32 v9, v0
	v_mov_b32_e32 v10, v0
	v_mov_b32_e32 v11, v0
	v_mov_b32_e32 v12, v0
	v_mov_b32_e32 v13, v0
	v_mov_b32_e32 v14, v0
	v_mov_b32_e32 v15, v0
	v_mov_b32_e32 v20, v0
	v_mov_b32_e32 v21, v0
	v_mov_b32_e32 v22, v0
	v_mov_b32_e32 v23, v0
	v_mov_b32_e32 v28, v0
	v_mov_b32_e32 v29, v0
	v_mov_b32_e32 v30, v0
	v_mov_b32_e32 v31, v0
	v_mov_b32_e32 v36, v0
	v_mov_b32_e32 v37, v0
	v_mov_b32_e32 v38, v0
	v_mov_b32_e32 v39, v0
	v_mov_b32_e32 v68, v0
	v_mov_b32_e32 v69, v0
	v_mov_b32_e32 v70, v0
	v_mov_b32_e32 v71, v0
	v_mov_b32_e32 v76, v0
	v_mov_b32_e32 v77, v0
	v_mov_b32_e32 v78, v0
	v_mov_b32_e32 v79, v0
	v_mov_b32_e32 v108, v0
	v_mov_b32_e32 v109, v0
	v_mov_b32_e32 v110, v0
	v_mov_b32_e32 v111, v0
	v_mov_b32_e32 v112, v0
	v_mov_b32_e32 v113, v0
	v_mov_b32_e32 v114, v0
	v_mov_b32_e32 v115, v0
	v_mov_b32_e32 v116, v0
	v_mov_b32_e32 v117, v0
	v_mov_b32_e32 v118, v0
	v_mov_b32_e32 v119, v0
	v_mov_b32_e32 v128, v0
	v_mov_b32_e32 v129, v0
	v_mov_b32_e32 v130, v0
	v_mov_b32_e32 v131, v0
	v_mov_b32_e32 v136, v0
	v_mov_b32_e32 v137, v0
	v_mov_b32_e32 v138, v0
	v_mov_b32_e32 v139, v0
	v_mov_b32_e32 v144, v0
	v_mov_b32_e32 v145, v0
	v_mov_b32_e32 v146, v0
	v_mov_b32_e32 v147, v0
	v_mov_b32_e32 v152, v0
	v_mov_b32_e32 v153, v0
	v_mov_b32_e32 v154, v0
	v_mov_b32_e32 v155, v0
	v_mov_b32_e32 v160, v0
	v_mov_b32_e32 v161, v0
	v_mov_b32_e32 v162, v0
	v_mov_b32_e32 v163, v0
	v_mov_b32_e32 v168, v0
	v_mov_b32_e32 v169, v0
	v_mov_b32_e32 v170, v0
	v_mov_b32_e32 v171, v0
	v_mov_b32_e32 v120, v0
	v_mov_b32_e32 v121, v0
	v_mov_b32_e32 v122, v0
	v_mov_b32_e32 v123, v0
	v_mov_b32_e32 v124, v0
	v_mov_b32_e32 v125, v0
	v_mov_b32_e32 v126, v0
	v_mov_b32_e32 v127, v0
	v_mov_b32_e32 v132, v0
	v_mov_b32_e32 v133, v0
	v_mov_b32_e32 v134, v0
	v_mov_b32_e32 v135, v0
	v_mov_b32_e32 v140, v0
	v_mov_b32_e32 v141, v0
	v_mov_b32_e32 v142, v0
	v_mov_b32_e32 v143, v0
	v_mov_b32_e32 v148, v0
	v_mov_b32_e32 v149, v0
	v_mov_b32_e32 v150, v0
	v_mov_b32_e32 v151, v0
	v_mov_b32_e32 v156, v0
	v_mov_b32_e32 v157, v0
	v_mov_b32_e32 v158, v0
	v_mov_b32_e32 v159, v0
	v_mov_b32_e32 v164, v0
	v_mov_b32_e32 v165, v0
	v_mov_b32_e32 v166, v0
	v_mov_b32_e32 v167, v0
	v_mov_b32_e32 v172, v0
	v_mov_b32_e32 v173, v0
	v_mov_b32_e32 v174, v0
	v_mov_b32_e32 v175, v0
	s_and_b32 s99, s61, 1
	s_lshl_b32 s99, s99, 12
	s_add_u32 s99, s99, 0x20000
	s_and_b32 s98, s33, 3
	s_lshl_b32 s98, s98, 10
	s_add_u32 s98, s98, s99
	v_lshl_add_u32 v80, s0, 7, v190
	v_ashrrev_i32_e32 v81, 31, v80
	v_lshlrev_b64 v[80:81], 2, v[80:81]
	s_mov_b32 exec_lo, 0x10001
	s_mov_b32 exec_hi, 0x10001
	s_mov_b32 m0, s98
	v_lshl_add_u64 v[82:83], s[20:21], 0, v[80:81]
	global_load_lds_dwordx4 v[82:83], off
	global_load_lds_dwordx4 v[82:83], off offset:16
	s_add_u32 m0, s98, 32
	v_lshl_add_u64 v[82:83], s[26:27], 0, v[80:81]
	global_load_lds_dwordx4 v[82:83], off
	global_load_lds_dwordx4 v[82:83], off offset:16
	s_add_u32 m0, s98, 64
	v_lshl_add_u64 v[82:83], s[28:29], 0, v[80:81]
	global_load_lds_dwordx4 v[82:83], off
	global_load_lds_dwordx4 v[82:83], off offset:16
	s_add_u32 m0, s98, 96
	v_lshl_add_u64 v[82:83], s[30:31], 0, v[80:81]
	global_load_lds_dwordx4 v[82:83], off
	global_load_lds_dwordx4 v[82:83], off offset:16
	s_add_u32 m0, s98, 128
	v_lshl_add_u64 v[82:83], s[34:35], 0, v[80:81]
	global_load_lds_dwordx4 v[82:83], off
	global_load_lds_dwordx4 v[82:83], off offset:16
	s_add_u32 m0, s98, 160
	v_lshl_add_u64 v[82:83], s[36:37], 0, v[80:81]
	global_load_lds_dwordx4 v[82:83], off
	global_load_lds_dwordx4 v[82:83], off offset:16
	s_mov_b64 exec, -1

;     __device__ __forceinline__ void operator()(const f32x4 (&acc)[2][2][4][2], const Unit& u, int wr, int wc, int fr, int fq) const {
;         const int cc0 = wc * 32 + 8 * fq;
;         const int jg0 = u.pn * 128 + cc0;
;         f32x4 wa2[2][3], wb2[2][3];
; #pragma unroll
;         for (int n = 0; n < 2; ++n)
; #pragma unroll
;             for (int t = 0; t < 3; ++t) { wa2[n][t] = *(const f32x4*)(cw + t * 11008 + jg0 + 4 * n); wb2[n][t] = *(const f32x4*)(cw + t * 11008 + 5504 + jg0 + 4 * n); }
;         asm volatile("" :: "v"(wa2[0][0]), "v"(wa2[0][1]), "v"(wa2[0][2]), "v"(wb2[0][0]), "v"(wb2[0][1]), "v"(wb2[0][2]), "v"(wa2[1][0]), "v"(wa2[1][1]), "v"(wa2[1][2]), "v"(wb2[1][0]), "v"(wb2[1][1]), "v"(wb2[1][2]));
.LBB0_1222:
	v_lshl_add_u32 v212, s0, 7, v190
	v_ashrrev_i32_e32 v213, 31, v212
	v_lshl_add_u32 v100, v190, 5, s99
	ds_read_b128 v[48:51], v100 offset:16
	ds_read_b128 v[84:87], v100
	ds_read_b128 v[44:47], v100 offset:48
	ds_read_b128 v[80:83], v100 offset:32
	ds_read_b128 v[56:59], v100 offset:80
	ds_read_b128 v[92:95], v100 offset:64
	ds_read_b128 v[52:55], v100 offset:112
	ds_read_b128 v[88:91], v100 offset:96
	ds_read_b128 v[60:63], v100 offset:144
	ds_read_b128 v[96:99], v100 offset:128
	ds_read_b128 v[64:67], v100 offset:176
	ds_read_b128 v[100:103], v100 offset:160
	v_mov_b32_dpp v176, v156 row_ror:15 row_mask:0xf bank_mask:0xf bound_ctrl:1
	v_mov_b32_dpp v177, v152 row_ror:15 row_mask:0xf bank_mask:0xf bound_ctrl:1
	s_ashr_i32 s13, s12, 31
	v_mov_b32_dpp v176, v172 row_shl:1 row_mask:0xf bank_mask:0xf
	v_mov_b32_dpp v177, v168 row_shl:1 row_mask:0xf bank_mask:0xf
	s_lshl_b64 s[46:47], s[12:13], 8
	s_add_u32 s41, s46, s62
	s_addc_u32 s39, s47, s65
	s_waitcnt lgkmcnt(0)
; __device__ __forceinline__ unsigned cvt_pk_bf16(float lo, float hi) { unsigned r; asm volatile("v_cvt_pk_bf16_f32 %0, %1, %2" : "=v"(r) : "v"(lo), "v"(hi)); return r; }
; template <int CTRL> __device__ __forceinline__ float dppmov(float x) { return __builtin_bit_cast(float, __builtin_amdgcn_mov_dpp(__builtin_bit_cast(int, x), CTRL, 0xf, 0xf, true)); }
; template <int CTRL> __device__ __forceinline__ float dppupd(float old, float x) { return __builtin_bit_cast(float, __builtin_amdgcn_update_dpp(__builtin_bit_cast(int, old), __builtin_bit_cast(int, x), CTRL, 0xf, 0xf, false)); }
;     __device__ __forceinline__ void operator()(const f32x4 (&acc)[2][2][4][2], const Unit& u, int wr, int wc, int fr, int fq) const {
;     ...
;                 for (int n = 0; n < 2; ++n) {
;                     const f32x4 (&wa)[3] = wa2[n]; const f32x4 (&wb)[3] = wb2[n];
;                     f32x4 ga;
; #pragma unroll
;                     for (int e = 0; e < 4; ++e) {
;                         const float ac = acc[ai][0][m][n][e], bc = acc[ai][1][m][n][e];
;                         const float apo = (m > 0) ? dppmov<0x121>(acc[ai][0][m > 0 ? m - 1 : 0][n][e]) : 0.f, bpo = (m > 0) ? dppmov<0x121>(acc[ai][1][m > 0 ? m - 1 : 0][n][e]) : 0.f;
;                         const float ano = (m < 3) ? dppmov<0x12F>(acc[ai][0][m < 3 ? m + 1 : 3][n][e]) : 0.f, bno = (m < 3) ? dppmov<0x12F>(acc[ai][1][m < 3 ? m + 1 : 3][n][e]) : 0.f;
;                         const float ap = dppupd<0x111>(apo, ac), bp = dppupd<0x111>(bpo, bc);
;                         const float an = dppupd<0x101>(ano, ac), bn = dppupd<0x101>(bno, bc);
;                         const float a = ap * wa[0][e] + ac * wa[1][e] + an * wa[2][e], b = bp * wb[0][e] + bc * wb[1][e] + bn * wb[2][e];
;                         ga[e] = a * __builtin_amdgcn_rcpf(1.f + __expf(-a)) * b;
;                     }
;                     gq[2 * n] = cvt_pk_bf16(ga[0], ga[1]); gq[2 * n + 1] = cvt_pk_bf16(ga[2], ga[3]);
;                 }
;                 const int sl = 16 * m + fr;
;                 const size_t row = (size_t)u.pm * BM + ai * HALF + wr * 64 + sl;
;                 if (sl != 0 && sl != 63) *(u32x4*)(G + row * 5504 + jg0) = (u32x4){gq[0], gq[1], gq[2], gq[3]};
	v_mul_f32_dpp v178, v172, v84 row_shr:1 row_mask:0xf bank_mask:0xf bound_ctrl:1
	v_fmac_f32_e32 v178, v172, v92
	v_fmac_f32_e32 v178, v96, v176
	v_mul_f32_dpp v176, v168, v80 row_shr:1 row_mask:0xf bank_mask:0xf bound_ctrl:1
	v_fmac_f32_e32 v176, v168, v88
	v_fmac_f32_e32 v176, v100, v177
	v_mul_f32_e32 v177, 0xbfb8aa3b, v178
	v_exp_f32_e32 v177, v177
	v_mul_f32_dpp v179, v173, v85 row_shr:1 row_mask:0xf bank_mask:0xf bound_ctrl:1
	v_fmac_f32_e32 v179, v173, v93
	v_mul_f32_dpp v214, v174, v86 row_shr:1 row_mask:0xf bank_mask:0xf bound_ctrl:1
	v_add_f32_e32 v177, 1.0, v177
	v_rcp_f32_e32 v177, v177
	v_fmac_f32_e32 v214, v174, v94
	v_mul_f32_dpp v215, v175, v87 row_shr:1 row_mask:0xf bank_mask:0xf bound_ctrl:1
	v_fmac_f32_e32 v215, v175, v95
	v_mul_f32_e32 v177, v178, v177
	v_mul_f32_e32 v176, v176, v177
	v_mov_b32_dpp v178, v153 row_ror:15 row_mask:0xf bank_mask:0xf bound_ctrl:1
	v_mov_b32_dpp v177, v157 row_ror:15 row_mask:0xf bank_mask:0xf bound_ctrl:1
	v_mul_f32_dpp v216, v166, v50 row_shr:1 row_mask:0xf bank_mask:0xf bound_ctrl:1
	v_mov_b32_dpp v178, v169 row_shl:1 row_mask:0xf bank_mask:0xf
	v_mov_b32_dpp v177, v173 row_shl:1 row_mask:0xf bank_mask:0xf
	v_fmac_f32_e32 v179, v97, v177
	v_fmac_f32_e32 v216, v166, v58
	v_mul_f32_dpp v177, v169, v81 row_shr:1 row_mask:0xf bank_mask:0xf bound_ctrl:1
	v_fmac_f32_e32 v177, v169, v89
	v_fmac_f32_e32 v177, v101, v178
	v_mul_f32_e32 v178, 0xbfb8aa3b, v179
	v_exp_f32_e32 v178, v178
	v_mul_f32_dpp v217, v167, v51 row_shr:1 row_mask:0xf bank_mask:0xf bound_ctrl:1
	v_fmac_f32_e32 v217, v167, v59
	v_add_f32_e32 v178, 1.0, v178
	v_rcp_f32_e32 v178, v178
	s_nop 0
	v_mul_f32_e32 v178, v179, v178
	v_mul_f32_e32 v177, v177, v178
	s_nop 0
	v_mov_b32_dpp v178, v158 row_ror:15 row_mask:0xf bank_mask:0xf bound_ctrl:1
	v_mov_b32_dpp v179, v154 row_ror:15 row_mask:0xf bank_mask:0xf bound_ctrl:1
	v_cvt_pk_bf16_f32 v176, v176, v177
	s_nop 0
	v_mov_b32_dpp v178, v174 row_shl:1 row_mask:0xf bank_mask:0xf
	v_fmac_f32_e32 v214, v98, v178
	v_mov_b32_dpp v179, v170 row_shl:1 row_mask:0xf bank_mask:0xf
	v_mul_f32_dpp v178, v170, v82 row_shr:1 row_mask:0xf bank_mask:0xf bound_ctrl:1
	v_fmac_f32_e32 v178, v170, v90
	v_fmac_f32_e32 v178, v102, v179
	v_mul_f32_e32 v179, 0xbfb8aa3b, v214
	v_exp_f32_e32 v179, v179
	s_nop 0
	v_add_f32_e32 v179, 1.0, v179
	v_rcp_f32_e32 v179, v179
	s_nop 0
	v_mul_f32_e32 v179, v214, v179
	v_mul_f32_e32 v178, v178, v179
	s_nop 0
	v_mov_b32_dpp v179, v159 row_ror:15 row_mask:0xf bank_mask:0xf bound_ctrl:1
	v_mov_b32_dpp v214, v155 row_ror:15 row_mask:0xf bank_mask:0xf bound_ctrl:1
	s_nop 0
	v_mov_b32_dpp v179, v175 row_shl:1 row_mask:0xf bank_mask:0xf
	v_fmac_f32_e32 v215, v99, v179
	v_mov_b32_dpp v214, v171 row_shl:1 row_mask:0xf bank_mask:0xf
	v_mul_f32_dpp v179, v171, v83 row_shr:1 row_mask:0xf bank_mask:0xf bound_ctrl:1
	v_fmac_f32_e32 v179, v171, v91
	v_fmac_f32_e32 v179, v103, v214
	v_mul_f32_e32 v214, 0xbfb8aa3b, v215
	v_exp_f32_e32 v214, v214
	s_nop 0
	v_add_f32_e32 v214, 1.0, v214
	v_rcp_f32_e32 v214, v214
	s_nop 0
	v_mul_f32_e32 v214, v215, v214
	v_mul_f32_e32 v179, v179, v214
	v_cvt_pk_bf16_f32 v177, v178, v179
	v_mov_b32_dpp v178, v148 row_ror:15 row_mask:0xf bank_mask:0xf bound_ctrl:1
	v_mul_f32_dpp v214, v164, v48 row_shr:1 row_mask:0xf bank_mask:0xf bound_ctrl:1
	v_fmac_f32_e32 v214, v164, v56
	v_mov_b32_dpp v178, v164 row_shl:1 row_mask:0xf bank_mask:0xf
	v_mov_b32_dpp v179, v144 row_ror:15 row_mask:0xf bank_mask:0xf bound_ctrl:1
	v_fmac_f32_e32 v214, v60, v178
	v_mul_f32_dpp v178, v160, v44 row_shr:1 row_mask:0xf bank_mask:0xf bound_ctrl:1
	v_mov_b32_dpp v179, v160 row_shl:1 row_mask:0xf bank_mask:0xf
	v_fmac_f32_e32 v178, v160, v52
	v_fmac_f32_e32 v178, v64, v179
	v_mul_f32_e32 v179, 0xbfb8aa3b, v214
	v_exp_f32_e32 v179, v179
	v_mul_f32_dpp v215, v165, v49 row_shr:1 row_mask:0xf bank_mask:0xf bound_ctrl:1
	v_fmac_f32_e32 v215, v165, v57
	v_add_f32_e32 v179, 1.0, v179
	v_rcp_f32_e32 v179, v179
	s_nop 0
	v_mul_f32_e32 v179, v214, v179
	v_mul_f32_e32 v178, v178, v179
	s_nop 0
	v_mov_b32_dpp v179, v149 row_ror:15 row_mask:0xf bank_mask:0xf bound_ctrl:1
	v_mov_b32_dpp v214, v145 row_ror:15 row_mask:0xf bank_mask:0xf bound_ctrl:1
	s_nop 0
	v_mov_b32_dpp v179, v165 row_shl:1 row_mask:0xf bank_mask:0xf
	v_fmac_f32_e32 v215, v61, v179
	v_mov_b32_dpp v214, v161 row_shl:1 row_mask:0xf bank_mask:0xf
	v_mul_f32_dpp v179, v161, v45 row_shr:1 row_mask:0xf bank_mask:0xf bound_ctrl:1
	v_fmac_f32_e32 v179, v161, v53
	v_fmac_f32_e32 v179, v65, v214
	v_mul_f32_e32 v214, 0xbfb8aa3b, v215
	v_exp_f32_e32 v214, v214
	s_nop 0
	v_add_f32_e32 v214, 1.0, v214
	v_rcp_f32_e32 v214, v214
	s_nop 0
	v_mul_f32_e32 v214, v215, v214
	v_mul_f32_e32 v179, v179, v214
	s_nop 0
	v_mov_b32_dpp v214, v150 row_ror:15 row_mask:0xf bank_mask:0xf bound_ctrl:1
	v_mov_b32_dpp v215, v146 row_ror:15 row_mask:0xf bank_mask:0xf bound_ctrl:1
	v_cvt_pk_bf16_f32 v178, v178, v179
	s_nop 0
	v_mov_b32_dpp v214, v166 row_shl:1 row_mask:0xf bank_mask:0xf
	v_fmac_f32_e32 v216, v62, v214
	v_mov_b32_dpp v215, v162 row_shl:1 row_mask:0xf bank_mask:0xf
	v_mul_f32_dpp v214, v162, v46 row_shr:1 row_mask:0xf bank_mask:0xf bound_ctrl:1
	v_fmac_f32_e32 v214, v162, v54
	v_fmac_f32_e32 v214, v66, v215
	v_mul_f32_e32 v215, 0xbfb8aa3b, v216
	v_exp_f32_e32 v215, v215
	s_nop 0
	v_add_f32_e32 v215, 1.0, v215
	v_rcp_f32_e32 v215, v215
	s_nop 0
	v_mul_f32_e32 v215, v216, v215
	v_mul_f32_e32 v214, v214, v215
	s_nop 0
	v_mov_b32_dpp v215, v151 row_ror:15 row_mask:0xf bank_mask:0xf bound_ctrl:1
	v_mov_b32_dpp v216, v147 row_ror:15 row_mask:0xf bank_mask:0xf bound_ctrl:1
	s_nop 0
	v_mov_b32_dpp v215, v167 row_shl:1 row_mask:0xf bank_mask:0xf
	v_fmac_f32_e32 v217, v63, v215
	v_mov_b32_dpp v216, v163 row_shl:1 row_mask:0xf bank_mask:0xf
	v_mul_f32_dpp v215, v163, v47 row_shr:1 row_mask:0xf bank_mask:0xf bound_ctrl:1
	v_fmac_f32_e32 v215, v163, v55
	v_fmac_f32_e32 v215, v67, v216
	v_mul_f32_e32 v216, 0xbfb8aa3b, v217
	v_exp_f32_e32 v216, v216
	s_nop 0
	v_add_f32_e32 v216, 1.0, v216
	v_rcp_f32_e32 v216, v216
	s_nop 0
	v_mul_f32_e32 v216, v217, v216
	v_mul_f32_e32 v215, v215, v216
	v_cvt_pk_bf16_f32 v179, v214, v215
	s_and_saveexec_b64 s[46:47], s[2:3]
	s_load_dword s72, s[94:95], 0xe8
	v_readlane_b32 s73, v255, 2
	s_cbranch_execz .LBB0_1224
	v_or_b32_e32 v216, s41, v188
	v_mov_b64_e32 v[214:215], s[16:17]
	v_mad_u64_u32 v[214:215], s[48:49], v216, s70, v[214:215]
	v_mad_i32_i24 v215, s39, v250, v215
	v_lshl_add_u64 v[214:215], v[212:213], 1, v[214:215]
	global_store_dwordx4 v[214:215], v[176:179], off

;     __host__ __device__ bool next(int i, Unit& u) const { const bool ok = StaticOrder::next(i, u); u.pm = 0; u.pn = 0; return ok; }
;     __device__ __forceinline__ void operator()(const f32x4 (&acc)[2][2][4][2], const Unit& u, int wr, int wc, int fr, int fq) const {
;     ...
;         f32x4 wa2[2][3], wb2[2][3];
; #pragma unroll
;         for (int n = 0; n < 2; ++n)
; #pragma unroll
;             for (int t = 0; t < 3; ++t) { wa2[n][t] = *(const f32x4*)(cw + t * 11008 + jg0 + 4 * n); wb2[n][t] = *(const f32x4*)(cw + t * 11008 + 5504 + jg0 + 4 * n); }
;         asm volatile("" :: "v"(wa2[0][0]), "v"(wa2[0][1]), "v"(wa2[0][2]), "v"(wb2[0][0]), "v"(wb2[0][1]), "v"(wb2[0][2]), "v"(wa2[1][0]), "v"(wa2[1][1]), "v"(wa2[1][2]), "v"(wb2[1][0]), "v"(wb2[1][1]), "v"(wb2[1][2]));
; template <class Epi, class Sched, bool ALIGN_EPI = false, bool SP2 = false>
; __device__ __forceinline__ void gemm_phase(PG8_LAS unsigned char* lds, const Gemm g, const Sched& S, const Epi& E, const int wave_in) {
;     ...
;     for (;;) {
;         const bool has_next = S.next(ui + 1, nxt);
;         const char* nA = has_next ? (const char*)g.A + (size_t)nxt.pm * tstepA : cA; const char* nB = has_next ? (const char*)g.Bt + (size_t)nxt.pn * tstepB : cB;
;         for (int t = 0; t < nt; t += 2) {
;             const bool last = (t == nt - 2);
;             const char* a1 = cA + (size_t)(t + 1) * kstep;
;             const char* a2 = last ? nA : cA + (size_t)(t + 2) * kstep; const char* b2 = last ? nB : cB + (size_t)(t + 2) * kstep;
;             const char* a3 = a2 + kstep; const char* b3 = b2 + kstep;
;             if (last && has_next) S.a_ready(nxt);
.LBB0_1950:
	s_ashr_i32 s41, s40, 31
	s_lshl_b64 s[42:43], s[40:41], 20
	s_add_u32 s42, s52, s42
	s_addc_u32 s43, s53, s43
	s_and_b64 s[44:45], s[10:11], exec
	s_cselect_b32 s1, s43, s47
	s_cselect_b32 s13, s42, s46
	s_ashr_i32 s39, s38, 31
	s_lshl_b64 s[44:45], s[38:39], 20
	s_add_u32 s44, s54, s44
	s_addc_u32 s45, s55, s45
	s_and_b64 s[50:51], s[10:11], exec
	s_cselect_b32 s39, s45, s49
	s_cselect_b32 s41, s44, s48
	s_add_u32 s46, s46, 0x80080
	s_addc_u32 s47, s47, 0
	s_add_u32 s72, s48, 0x100
	v_mov_b32_e32 v0, 0
	s_addc_u32 s73, s49, 0
	s_mov_b32 s74, -2
	v_mov_b32_e32 v1, v0
	v_mov_b32_e32 v2, v0
	v_mov_b32_e32 v3, v0
	v_mov_b32_e32 v4, v0
	v_mov_b32_e32 v5, v0
	v_mov_b32_e32 v6, v0
	v_mov_b32_e32 v7, v0
	v_mov_b32_e32 v16, v0
	v_mov_b32_e32 v17, v0
	v_mov_b32_e32 v18, v0
	v_mov_b32_e32 v19, v0
	v_mov_b32_e32 v24, v0
	v_mov_b32_e32 v25, v0
	v_mov_b32_e32 v26, v0
	v_mov_b32_e32 v27, v0
	v_mov_b32_e32 v32, v0
	v_mov_b32_e32 v33, v0
	v_mov_b32_e32 v34, v0
	v_mov_b32_e32 v35, v0
	v_mov_b32_e32 v40, v0
	v_mov_b32_e32 v41, v0
	v_mov_b32_e32 v42, v0
	v_mov_b32_e32 v43, v0
	v_mov_b32_e32 v72, v0
	v_mov_b32_e32 v73, v0
	v_mov_b32_e32 v74, v0
	v_mov_b32_e32 v75, v0
	v_mov_b32_e32 v104, v0
	v_mov_b32_e32 v105, v0
	v_mov_b32_e32 v106, v0
	v_mov_b32_e32 v107, v0
	v_mov_b32_e32 v8, v0
	v_mov_b32_e32 v9, v0
	v_mov_b32_e32 v10, v0
	v_mov_b32_e32 v11, v0
	v_mov_b32_e32 v12, v0
	v_mov_b32_e32 v13, v0
	v_mov_b32_e32 v14, v0
	v_mov_b32_e32 v15, v0
	v_mov_b32_e32 v20, v0
	v_mov_b32_e32 v21, v0
	v_mov_b32_e32 v22, v0
	v_mov_b32_e32 v23, v0
	v_mov_b32_e32 v28, v0
	v_mov_b32_e32 v29, v0
	v_mov_b32_e32 v30, v0
	v_mov_b32_e32 v31, v0
	v_mov_b32_e32 v36, v0
	v_mov_b32_e32 v37, v0
	v_mov_b32_e32 v38, v0
	v_mov_b32_e32 v39, v0
	v_mov_b32_e32 v68, v0
	v_mov_b32_e32 v69, v0
	v_mov_b32_e32 v70, v0
	v_mov_b32_e32 v71, v0
	v_mov_b32_e32 v76, v0
	v_mov_b32_e32 v77, v0
	v_mov_b32_e32 v78, v0
	v_mov_b32_e32 v79, v0
	v_mov_b32_e32 v108, v0
	v_mov_b32_e32 v109, v0
	v_mov_b32_e32 v110, v0
	v_mov_b32_e32 v111, v0
	v_mov_b32_e32 v112, v0
	v_mov_b32_e32 v113, v0
	s_waitcnt vmcnt(0)
	v_mov_b32_e32 v114, v0
	v_mov_b32_e32 v115, v0
	v_mov_b32_e32 v116, v0
	v_mov_b32_e32 v117, v0
	v_mov_b32_e32 v118, v0
	v_mov_b32_e32 v119, v0
	v_mov_b32_e32 v128, v0
	v_mov_b32_e32 v129, v0
	v_mov_b32_e32 v130, v0
	v_mov_b32_e32 v131, v0
	v_mov_b32_e32 v136, v0
	v_mov_b32_e32 v137, v0
	v_mov_b32_e32 v138, v0
	v_mov_b32_e32 v139, v0
	v_mov_b32_e32 v144, v0
	v_mov_b32_e32 v145, v0
	v_mov_b32_e32 v146, v0
	v_mov_b32_e32 v147, v0
	v_mov_b32_e32 v152, v0
	v_mov_b32_e32 v153, v0
	v_mov_b32_e32 v154, v0
	v_mov_b32_e32 v155, v0
	v_mov_b32_e32 v160, v0
	v_mov_b32_e32 v161, v0
	v_mov_b32_e32 v162, v0
	v_mov_b32_e32 v163, v0
	v_mov_b32_e32 v168, v0
	v_mov_b32_e32 v169, v0
	v_mov_b32_e32 v170, v0
	v_mov_b32_e32 v171, v0
	v_mov_b32_e32 v120, v0
	v_mov_b32_e32 v121, v0
	v_mov_b32_e32 v122, v0
	v_mov_b32_e32 v123, v0
	v_mov_b32_e32 v124, v0
	v_mov_b32_e32 v125, v0
	v_mov_b32_e32 v126, v0
	v_mov_b32_e32 v127, v0
	v_mov_b32_e32 v132, v0
	v_mov_b32_e32 v133, v0
	v_mov_b32_e32 v134, v0
	v_mov_b32_e32 v135, v0
	v_mov_b32_e32 v140, v0
	v_mov_b32_e32 v141, v0
	v_mov_b32_e32 v142, v0
	v_mov_b32_e32 v143, v0
	v_mov_b32_e32 v148, v0
	v_mov_b32_e32 v149, v0
	v_mov_b32_e32 v150, v0
	v_mov_b32_e32 v151, v0
	v_mov_b32_e32 v156, v0
	v_mov_b32_e32 v157, v0
	v_mov_b32_e32 v158, v0
	v_mov_b32_e32 v159, v0
	v_mov_b32_e32 v164, v0
	v_mov_b32_e32 v165, v0
	v_mov_b32_e32 v166, v0
	v_mov_b32_e32 v167, v0
	v_mov_b32_e32 v172, v0
	v_mov_b32_e32 v173, v0
	v_mov_b32_e32 v174, v0
	v_mov_b32_e32 v175, v0
	s_and_b32 s99, s61, 1
	s_lshl_b32 s99, s99, 12
	s_add_u32 s99, s99, 0x20000
	s_and_b32 s98, s33, 3
	s_lshl_b32 s98, s98, 10
	s_add_u32 s98, s98, s99
	v_lshl_add_u32 v80, s0, 7, v190
	v_ashrrev_i32_e32 v81, 31, v80
	v_lshlrev_b64 v[80:81], 2, v[80:81]
	s_mov_b32 exec_lo, 0x10001
	s_mov_b32 exec_hi, 0x10001
	s_mov_b32 m0, s98
	v_lshl_add_u64 v[82:83], s[20:21], 0, v[80:81]
	global_load_lds_dwordx4 v[82:83], off
	global_load_lds_dwordx4 v[82:83], off offset:16
	s_add_u32 m0, s98, 32
	v_lshl_add_u64 v[82:83], s[26:27], 0, v[80:81]
	global_load_lds_dwordx4 v[82:83], off
	global_load_lds_dwordx4 v[82:83], off offset:16
	s_add_u32 m0, s98, 64
	v_lshl_add_u64 v[82:83], s[28:29], 0, v[80:81]
	global_load_lds_dwordx4 v[82:83], off
	global_load_lds_dwordx4 v[82:83], off offset:16
	s_add_u32 m0, s98, 96
	v_lshl_add_u64 v[82:83], s[30:31], 0, v[80:81]
	global_load_lds_dwordx4 v[82:83], off
	global_load_lds_dwordx4 v[82:83], off offset:16
	s_add_u32 m0, s98, 128
	v_lshl_add_u64 v[82:83], s[34:35], 0, v[80:81]
	global_load_lds_dwordx4 v[82:83], off
	global_load_lds_dwordx4 v[82:83], off offset:16
	s_add_u32 m0, s98, 160
	v_lshl_add_u64 v[82:83], s[36:37], 0, v[80:81]
	global_load_lds_dwordx4 v[82:83], off
	global_load_lds_dwordx4 v[82:83], off offset:16
	s_mov_b64 exec, -1

;     __host__ __device__ bool next(int i, Unit& u) const { const bool ok = StaticOrder::next(i, u); u.pm = 0; u.pn = 0; return ok; }
;     __device__ __forceinline__ void operator()(const f32x4 (&acc)[2][2][4][2], const Unit& u, int wr, int wc, int fr, int fq) const {
;     ...
;         f32x4 wa2[2][3], wb2[2][3];
; #pragma unroll
;         for (int n = 0; n < 2; ++n)
; #pragma unroll
;             for (int t = 0; t < 3; ++t) { wa2[n][t] = *(const f32x4*)(cw + t * 11008 + jg0 + 4 * n); wb2[n][t] = *(const f32x4*)(cw + t * 11008 + 5504 + jg0 + 4 * n); }
;         asm volatile("" :: "v"(wa2[0][0]), "v"(wa2[0][1]), "v"(wa2[0][2]), "v"(wb2[0][0]), "v"(wb2[0][1]), "v"(wb2[0][2]), "v"(wa2[1][0]), "v"(wa2[1][1]), "v"(wa2[1][2]), "v"(wb2[1][0]), "v"(wb2[1][1]), "v"(wb2[1][2]));
; template <class Epi, class Sched, bool ALIGN_EPI = false, bool SP2 = false>
; __device__ __forceinline__ void gemm_phase(PG8_LAS unsigned char* lds, const Gemm g, const Sched& S, const Epi& E, const int wave_in) {
;     ...
;     for (;;) {
;         const bool has_next = S.next(ui + 1, nxt);
;         const char* nA = has_next ? (const char*)g.A + (size_t)nxt.pm * tstepA : cA; const char* nB = has_next ? (const char*)g.Bt + (size_t)nxt.pn * tstepB : cB;
;         for (int t = 0; t < nt; t += 2) {
;             const bool last = (t == nt - 2);
;             const char* a1 = cA + (size_t)(t + 1) * kstep;
;             const char* a2 = last ? nA : cA + (size_t)(t + 2) * kstep; const char* b2 = last ? nB : cB + (size_t)(t + 2) * kstep;
;             const char* a3 = a2 + kstep; const char* b3 = b2 + kstep;
;             if (last && has_next) S.a_ready(nxt);
.LBB0_2576:
	s_ashr_i32 s39, s38, 31
	s_lshl_b64 s[40:41], s[38:39], 20
	s_add_u32 s40, s52, s40
	s_addc_u32 s41, s53, s41
	s_and_b64 s[42:43], s[8:9], exec
	s_cselect_b32 s11, s41, s47
	s_cselect_b32 s39, s40, s46
	s_ashr_i32 s37, s36, 31
	s_lshl_b64 s[42:43], s[36:37], 20
	s_add_u32 s42, s54, s42
	s_addc_u32 s43, s55, s43
	s_and_b64 s[50:51], s[8:9], exec
	s_cselect_b32 s37, s43, s49
	s_cselect_b32 s45, s42, s48
	s_add_u32 s46, s46, 0x80080
	s_addc_u32 s47, s47, 0
	s_add_u32 s72, s48, 0x100
	v_mov_b32_e32 v0, 0
	s_addc_u32 s73, s49, 0
	s_mov_b32 s75, -2
	v_mov_b32_e32 v1, v0
	v_mov_b32_e32 v2, v0
	v_mov_b32_e32 v3, v0
	v_mov_b32_e32 v4, v0
	v_mov_b32_e32 v5, v0
	v_mov_b32_e32 v6, v0
	v_mov_b32_e32 v7, v0
	v_mov_b32_e32 v16, v0
	v_mov_b32_e32 v17, v0
	v_mov_b32_e32 v18, v0
	v_mov_b32_e32 v19, v0
	v_mov_b32_e32 v24, v0
	v_mov_b32_e32 v25, v0
	v_mov_b32_e32 v26, v0
	v_mov_b32_e32 v27, v0
	v_mov_b32_e32 v32, v0
	v_mov_b32_e32 v33, v0
	v_mov_b32_e32 v34, v0
	v_mov_b32_e32 v35, v0
	v_mov_b32_e32 v40, v0
	v_mov_b32_e32 v41, v0
	v_mov_b32_e32 v42, v0
	v_mov_b32_e32 v43, v0
	v_mov_b32_e32 v48, v0
	v_mov_b32_e32 v49, v0
	v_mov_b32_e32 v50, v0
	v_mov_b32_e32 v51, v0
	v_mov_b32_e32 v56, v0
	v_mov_b32_e32 v57, v0
	v_mov_b32_e32 v58, v0
	v_mov_b32_e32 v59, v0
	v_mov_b32_e32 v8, v0
	v_mov_b32_e32 v9, v0
	v_mov_b32_e32 v10, v0
	v_mov_b32_e32 v11, v0
	v_mov_b32_e32 v12, v0
	v_mov_b32_e32 v13, v0
	v_mov_b32_e32 v14, v0
	v_mov_b32_e32 v15, v0
	v_mov_b32_e32 v20, v0
	v_mov_b32_e32 v21, v0
	v_mov_b32_e32 v22, v0
	v_mov_b32_e32 v23, v0
	v_mov_b32_e32 v28, v0
	v_mov_b32_e32 v29, v0
	v_mov_b32_e32 v30, v0
	v_mov_b32_e32 v31, v0
	v_mov_b32_e32 v36, v0
	v_mov_b32_e32 v37, v0
	v_mov_b32_e32 v38, v0
	v_mov_b32_e32 v39, v0
	v_mov_b32_e32 v44, v0
	v_mov_b32_e32 v45, v0
	v_mov_b32_e32 v46, v0
	v_mov_b32_e32 v47, v0
	v_mov_b32_e32 v52, v0
	v_mov_b32_e32 v53, v0
	v_mov_b32_e32 v54, v0
	v_mov_b32_e32 v55, v0
	v_mov_b32_e32 v60, v0
	v_mov_b32_e32 v61, v0
	v_mov_b32_e32 v62, v0
	v_mov_b32_e32 v63, v0
	v_mov_b32_e32 v112, v0
	v_mov_b32_e32 v113, v0
	s_waitcnt vmcnt(0)
	v_mov_b32_e32 v114, v0
	v_mov_b32_e32 v115, v0
	v_mov_b32_e32 v116, v0
	v_mov_b32_e32 v117, v0
	v_mov_b32_e32 v118, v0
	v_mov_b32_e32 v119, v0
	v_mov_b32_e32 v128, v0
	v_mov_b32_e32 v129, v0
	v_mov_b32_e32 v130, v0
	v_mov_b32_e32 v131, v0
	v_mov_b32_e32 v136, v0
	v_mov_b32_e32 v137, v0
	v_mov_b32_e32 v138, v0
	v_mov_b32_e32 v139, v0
	v_mov_b32_e32 v144, v0
	v_mov_b32_e32 v145, v0
	v_mov_b32_e32 v146, v0
	v_mov_b32_e32 v147, v0
	v_mov_b32_e32 v152, v0
	v_mov_b32_e32 v153, v0
	v_mov_b32_e32 v154, v0
	v_mov_b32_e32 v155, v0
	v_mov_b32_e32 v160, v0
	v_mov_b32_e32 v161, v0
	v_mov_b32_e32 v162, v0
	v_mov_b32_e32 v163, v0
	v_mov_b32_e32 v168, v0
	v_mov_b32_e32 v169, v0
	v_mov_b32_e32 v170, v0
	v_mov_b32_e32 v171, v0
	v_mov_b32_e32 v120, v0
	v_mov_b32_e32 v121, v0
	v_mov_b32_e32 v122, v0
	v_mov_b32_e32 v123, v0
	v_mov_b32_e32 v124, v0
	v_mov_b32_e32 v125, v0
	v_mov_b32_e32 v126, v0
	v_mov_b32_e32 v127, v0
	v_mov_b32_e32 v132, v0
	v_mov_b32_e32 v133, v0
	v_mov_b32_e32 v134, v0
	v_mov_b32_e32 v135, v0
	v_mov_b32_e32 v140, v0
	v_mov_b32_e32 v141, v0
	v_mov_b32_e32 v142, v0
	v_mov_b32_e32 v143, v0
	v_mov_b32_e32 v148, v0
	v_mov_b32_e32 v149, v0
	v_mov_b32_e32 v150, v0
	v_mov_b32_e32 v151, v0
	v_mov_b32_e32 v156, v0
	v_mov_b32_e32 v157, v0
	v_mov_b32_e32 v158, v0
	v_mov_b32_e32 v159, v0
	v_mov_b32_e32 v164, v0
	v_mov_b32_e32 v165, v0
	v_mov_b32_e32 v166, v0
	v_mov_b32_e32 v167, v0
	v_mov_b32_e32 v172, v0
	v_mov_b32_e32 v173, v0
	v_mov_b32_e32 v174, v0
	v_mov_b32_e32 v175, v0
	s_and_b32 s99, s61, 1
	s_lshl_b32 s99, s99, 12
	s_add_u32 s99, s99, 0x20000
	s_and_b32 s98, s33, 3
	s_lshl_b32 s98, s98, 10
	s_add_u32 s98, s98, s99
	v_lshl_add_u32 v80, s44, 7, v190
	v_ashrrev_i32_e32 v81, 31, v80
	v_lshlrev_b64 v[80:81], 2, v[80:81]
	s_mov_b32 exec_lo, 0x10001
	s_mov_b32 exec_hi, 0x10001
	s_mov_b32 m0, s98
	v_lshl_add_u64 v[82:83], s[18:19], 0, v[80:81]
	global_load_lds_dwordx4 v[82:83], off
	global_load_lds_dwordx4 v[82:83], off offset:16
	s_add_u32 m0, s98, 32
	v_lshl_add_u64 v[82:83], s[24:25], 0, v[80:81]
	global_load_lds_dwordx4 v[82:83], off
	global_load_lds_dwordx4 v[82:83], off offset:16
	s_add_u32 m0, s98, 64
	v_lshl_add_u64 v[82:83], s[26:27], 0, v[80:81]
	global_load_lds_dwordx4 v[82:83], off
	global_load_lds_dwordx4 v[82:83], off offset:16
	s_add_u32 m0, s98, 96
	v_lshl_add_u64 v[82:83], s[28:29], 0, v[80:81]
	global_load_lds_dwordx4 v[82:83], off
	global_load_lds_dwordx4 v[82:83], off offset:16
	s_add_u32 m0, s98, 128
	v_lshl_add_u64 v[82:83], s[30:31], 0, v[80:81]
	global_load_lds_dwordx4 v[82:83], off
	global_load_lds_dwordx4 v[82:83], off offset:16
	s_add_u32 m0, s98, 160
	v_lshl_add_u64 v[82:83], s[34:35], 0, v[80:81]
	global_load_lds_dwordx4 v[82:83], off
	global_load_lds_dwordx4 v[82:83], off offset:16
	s_mov_b64 exec, -1

;     __device__ __forceinline__ void operator()(const f32x4 (&acc)[2][2][4][2], const Unit& u, int wr, int wc, int fr, int fq) const {
;         const int cc0 = wc * 32 + 8 * fq;
;         const int jg0 = u.pn * 128 + cc0;
;         f32x4 wa2[2][3], wb2[2][3];
; #pragma unroll
;         for (int n = 0; n < 2; ++n)
; #pragma unroll
;             for (int t = 0; t < 3; ++t) { wa2[n][t] = *(const f32x4*)(cw + t * 11008 + jg0 + 4 * n); wb2[n][t] = *(const f32x4*)(cw + t * 11008 + 5504 + jg0 + 4 * n); }
;         asm volatile("" :: "v"(wa2[0][0]), "v"(wa2[0][1]), "v"(wa2[0][2]), "v"(wb2[0][0]), "v"(wb2[0][1]), "v"(wb2[0][2]), "v"(wa2[1][0]), "v"(wa2[1][1]), "v"(wa2[1][2]), "v"(wb2[1][0]), "v"(wb2[1][1]), "v"(wb2[1][2]));
; #pragma unroll
;         for (int ai = 0; ai < 2; ++ai)
; #pragma unroll
;             for (int m = 0; m < 4; ++m) {
;                 unsigned gq[4];
; #pragma unroll
;                 for (int n = 0; n < 2; ++n) {
;                     const f32x4 (&wa)[3] = wa2[n]; const f32x4 (&wb)[3] = wb2[n];
;                     f32x4 ga;
; #pragma unroll
;                     for (int e = 0; e < 4; ++e) {
;                         const float ac = acc[ai][0][m][n][e], bc = acc[ai][1][m][n][e];
;                         const float apo = (m > 0) ? dppmov<0x121>(acc[ai][0][m > 0 ? m - 1 : 0][n][e]) : 0.f, bpo = (m > 0) ? dppmov<0x121>(acc[ai][1][m > 0 ? m - 1 : 0][n][e]) : 0.f;
;                         const float ano = (m < 3) ? dppmov<0x12F>(acc[ai][0][m < 3 ? m + 1 : 3][n][e]) : 0.f, bno = (m < 3) ? dppmov<0x12F>(acc[ai][1][m < 3 ? m + 1 : 3][n][e]) : 0.f;
;                         const float ap = dppupd<0x111>(apo, ac), bp = dppupd<0x111>(bpo, bc);
;                         const float an = dppupd<0x101>(ano, ac), bn = dppupd<0x101>(bno, bc);
;                         const float a = ap * wa[0][e] + ac * wa[1][e] + an * wa[2][e], b = bp * wb[0][e] + bc * wb[1][e] + bn * wb[2][e];
;                         ga[e] = a * __builtin_amdgcn_rcpf(1.f + __expf(-a)) * b;
;                     }
;                     gq[2 * n] = cvt_pk_bf16(ga[0], ga[1]); gq[2 * n + 1] = cvt_pk_bf16(ga[2], ga[3]);
;                 }
;                 const int sl = 16 * m + fr;
;                 const size_t row = (size_t)u.pm * BM + ai * HALF + wr * 64 + sl;
;                 if (sl != 0 && sl != 63) *(u32x4*)(G + row * 5504 + jg0) = (u32x4){gq[0], gq[1], gq[2], gq[3]};
.LBB0_2580:
	v_lshl_add_u32 v212, s44, 7, v190
	v_ashrrev_i32_e32 v213, 31, v212
	v_lshl_add_u32 v96, v190, 5, s99
	ds_read_b128 v[76:79], v96 offset:16
	ds_read_b128 v[100:103], v96
	ds_read_b128 v[64:67], v96 offset:48
	ds_read_b128 v[88:91], v96 offset:32
	ds_read_b128 v[80:83], v96 offset:80
	ds_read_b128 v[104:107], v96 offset:64
	ds_read_b128 v[68:71], v96 offset:112
	ds_read_b128 v[92:95], v96 offset:96
	ds_read_b128 v[84:87], v96 offset:144
	ds_read_b128 v[108:111], v96 offset:128
	ds_read_b128 v[72:75], v96 offset:176
	ds_read_b128 v[96:99], v96 offset:160
	v_mov_b32_dpp v176, v156 row_ror:15 row_mask:0xf bank_mask:0xf bound_ctrl:1
	v_mov_b32_dpp v178, v157 row_ror:15 row_mask:0xf bank_mask:0xf bound_ctrl:1
	v_mov_b32_dpp v214, v158 row_ror:15 row_mask:0xf bank_mask:0xf bound_ctrl:1
	v_mov_b32_dpp v177, v152 row_ror:15 row_mask:0xf bank_mask:0xf bound_ctrl:1
	v_mov_b32_dpp v216, v159 row_ror:15 row_mask:0xf bank_mask:0xf bound_ctrl:1
	v_mov_b32_dpp v176, v172 row_shl:1 row_mask:0xf bank_mask:0xf
	v_mov_b32_dpp v178, v173 row_shl:1 row_mask:0xf bank_mask:0xf
	v_mov_b32_dpp v214, v174 row_shl:1 row_mask:0xf bank_mask:0xf
	v_mov_b32_dpp v179, v153 row_ror:15 row_mask:0xf bank_mask:0xf bound_ctrl:1
	v_mov_b32_dpp v177, v168 row_shl:1 row_mask:0xf bank_mask:0xf
	v_mov_b32_dpp v216, v175 row_shl:1 row_mask:0xf bank_mask:0xf
	v_mov_b32_dpp v179, v169 row_shl:1 row_mask:0xf bank_mask:0xf
	v_mov_b32_dpp v218, v148 row_ror:15 row_mask:0xf bank_mask:0xf bound_ctrl:1
	v_mov_b32_dpp v215, v154 row_ror:15 row_mask:0xf bank_mask:0xf bound_ctrl:1
	v_mov_b32_dpp v217, v155 row_ror:15 row_mask:0xf bank_mask:0xf bound_ctrl:1
	v_mov_b32_dpp v218, v164 row_shl:1 row_mask:0xf bank_mask:0xf
	v_mov_b32_dpp v215, v170 row_shl:1 row_mask:0xf bank_mask:0xf
	v_mov_b32_dpp v217, v171 row_shl:1 row_mask:0xf bank_mask:0xf
	v_mov_b32_dpp v219, v144 row_ror:15 row_mask:0xf bank_mask:0xf bound_ctrl:1
	s_ashr_i32 s11, s10, 31
	s_lshl_b64 s[46:47], s[10:11], 8
	v_mov_b32_dpp v219, v160 row_shl:1 row_mask:0xf bank_mask:0xf
	s_add_u32 s39, s46, s62
	s_addc_u32 s37, s47, s65
	s_waitcnt lgkmcnt(0)
	v_mul_f32_dpp v220, v172, v100 row_shr:1 row_mask:0xf bank_mask:0xf bound_ctrl:1
	v_mul_f32_dpp v222, v173, v101 row_shr:1 row_mask:0xf bank_mask:0xf bound_ctrl:1
	v_mul_f32_dpp v224, v174, v102 row_shr:1 row_mask:0xf bank_mask:0xf bound_ctrl:1
	v_mul_f32_dpp v221, v168, v88 row_shr:1 row_mask:0xf bank_mask:0xf bound_ctrl:1
	v_mul_f32_dpp v226, v175, v103 row_shr:1 row_mask:0xf bank_mask:0xf bound_ctrl:1
	v_fmac_f32_e32 v220, v172, v104
	v_fmac_f32_e32 v222, v173, v105
	v_fmac_f32_e32 v224, v174, v106
	v_mul_f32_dpp v223, v169, v89 row_shr:1 row_mask:0xf bank_mask:0xf bound_ctrl:1
	v_fmac_f32_e32 v221, v168, v92
	v_fmac_f32_e32 v226, v175, v107
	v_fmac_f32_e32 v220, v108, v176
	v_fmac_f32_e32 v222, v109, v178
	v_fmac_f32_e32 v224, v110, v214
	v_fmac_f32_e32 v223, v169, v93
	v_fmac_f32_e32 v221, v96, v177
	v_fmac_f32_e32 v226, v111, v216
	v_mul_f32_e32 v176, 0xbfb8aa3b, v220
	v_mul_f32_e32 v177, 0xbfb8aa3b, v222
	v_mul_f32_e32 v178, 0xbfb8aa3b, v224
	v_fmac_f32_e32 v223, v97, v179
	v_mul_f32_e32 v179, 0xbfb8aa3b, v226
	v_exp_f32_e32 v176, v176
	v_exp_f32_e32 v177, v177
	v_exp_f32_e32 v178, v178
	v_exp_f32_e32 v179, v179
	v_mul_f32_dpp v228, v164, v76 row_shr:1 row_mask:0xf bank_mask:0xf bound_ctrl:1
	v_fmac_f32_e32 v228, v164, v80
	v_add_f32_e32 v176, 1.0, v176
	v_add_f32_e32 v177, 1.0, v177
	v_add_f32_e32 v178, 1.0, v178
	v_fmac_f32_e32 v228, v84, v218
	v_add_f32_e32 v179, 1.0, v179
	v_rcp_f32_e32 v176, v176
	v_rcp_f32_e32 v177, v177
	v_rcp_f32_e32 v178, v178
	v_mul_f32_e32 v214, 0xbfb8aa3b, v228
	v_rcp_f32_e32 v179, v179
	v_mul_f32_dpp v225, v170, v90 row_shr:1 row_mask:0xf bank_mask:0xf bound_ctrl:1
	v_exp_f32_e32 v214, v214
	v_mul_f32_dpp v227, v171, v91 row_shr:1 row_mask:0xf bank_mask:0xf bound_ctrl:1
	v_fmac_f32_e32 v225, v170, v94
	v_fmac_f32_e32 v227, v171, v95
	v_fmac_f32_e32 v225, v98, v215
	v_mul_f32_e32 v176, v220, v176
	v_mul_f32_e32 v177, v222, v177
	v_mul_f32_e32 v178, v224, v178
	v_fmac_f32_e32 v227, v99, v217
	v_mul_f32_e32 v179, v226, v179
	v_mul_f32_e32 v176, v221, v176
	v_mul_f32_e32 v177, v223, v177
	v_mul_f32_e32 v178, v225, v178
	v_mul_f32_e32 v179, v227, v179
	v_cvt_pk_bf16_f32 v176, v176, v177
	v_cvt_pk_bf16_f32 v177, v178, v179
	v_add_f32_e32 v178, 1.0, v214
	v_mov_b32_dpp v214, v149 row_ror:15 row_mask:0xf bank_mask:0xf bound_ctrl:1
	v_mul_f32_dpp v215, v165, v77 row_shr:1 row_mask:0xf bank_mask:0xf bound_ctrl:1
	v_fmac_f32_e32 v215, v165, v81
	v_mov_b32_dpp v214, v165 row_shl:1 row_mask:0xf bank_mask:0xf
	v_fmac_f32_e32 v215, v85, v214
	v_mul_f32_e32 v214, 0xbfb8aa3b, v215
	v_exp_f32_e32 v214, v214
	v_rcp_f32_e32 v178, v178
	v_mul_f32_dpp v179, v160, v64 row_shr:1 row_mask:0xf bank_mask:0xf bound_ctrl:1
	v_fmac_f32_e32 v179, v160, v68
	v_add_f32_e32 v214, 1.0, v214
	v_rcp_f32_e32 v214, v214
	v_fmac_f32_e32 v179, v72, v219
	v_mul_f32_e32 v178, v228, v178
	v_mul_f32_e32 v178, v179, v178
	v_mov_b32_dpp v179, v145 row_ror:15 row_mask:0xf bank_mask:0xf bound_ctrl:1
	v_mul_f32_dpp v216, v161, v65 row_shr:1 row_mask:0xf bank_mask:0xf bound_ctrl:1
	v_fmac_f32_e32 v216, v161, v69
	v_mov_b32_dpp v179, v161 row_shl:1 row_mask:0xf bank_mask:0xf
	v_fmac_f32_e32 v216, v73, v179
	v_mul_f32_e32 v179, v215, v214
	v_mov_b32_dpp v214, v150 row_ror:15 row_mask:0xf bank_mask:0xf bound_ctrl:1
	v_mul_f32_dpp v215, v166, v78 row_shr:1 row_mask:0xf bank_mask:0xf bound_ctrl:1
	v_fmac_f32_e32 v215, v166, v82
	v_mov_b32_dpp v214, v166 row_shl:1 row_mask:0xf bank_mask:0xf
	v_fmac_f32_e32 v215, v86, v214
	v_mul_f32_e32 v214, 0xbfb8aa3b, v215
	v_exp_f32_e32 v214, v214
	v_mul_f32_e32 v179, v216, v179
	v_mov_b32_dpp v216, v146 row_ror:15 row_mask:0xf bank_mask:0xf bound_ctrl:1
	v_mul_f32_dpp v217, v162, v66 row_shr:1 row_mask:0xf bank_mask:0xf bound_ctrl:1
	v_add_f32_e32 v214, 1.0, v214
	v_rcp_f32_e32 v214, v214
	v_mov_b32_dpp v216, v162 row_shl:1 row_mask:0xf bank_mask:0xf
	v_fmac_f32_e32 v217, v162, v70
	v_fmac_f32_e32 v217, v74, v216
	v_mul_f32_e32 v214, v215, v214
	v_mov_b32_dpp v215, v151 row_ror:15 row_mask:0xf bank_mask:0xf bound_ctrl:1
	v_mul_f32_dpp v216, v167, v79 row_shr:1 row_mask:0xf bank_mask:0xf bound_ctrl:1
	v_fmac_f32_e32 v216, v167, v83
	v_mov_b32_dpp v215, v167 row_shl:1 row_mask:0xf bank_mask:0xf
	v_fmac_f32_e32 v216, v87, v215
	v_mul_f32_e32 v215, 0xbfb8aa3b, v216
	v_exp_f32_e32 v215, v215
	v_mul_f32_e32 v214, v217, v214
	v_mov_b32_dpp v217, v147 row_ror:15 row_mask:0xf bank_mask:0xf bound_ctrl:1
	v_mul_f32_dpp v218, v163, v67 row_shr:1 row_mask:0xf bank_mask:0xf bound_ctrl:1
	v_add_f32_e32 v215, 1.0, v215
	v_rcp_f32_e32 v215, v215
	v_mov_b32_dpp v217, v163 row_shl:1 row_mask:0xf bank_mask:0xf
	v_fmac_f32_e32 v218, v163, v71
	v_fmac_f32_e32 v218, v75, v217
	v_mul_f32_e32 v215, v216, v215
	v_mul_f32_e32 v215, v218, v215
	v_cvt_pk_bf16_f32 v178, v178, v179
	v_cvt_pk_bf16_f32 v179, v214, v215
	s_and_saveexec_b64 s[46:47], s[0:1]
	v_readlane_b32 s72, v255, 1
	v_readlane_b32 s73, v255, 2
	s_cbranch_execz .LBB0_2582
;     __device__ __forceinline__ void operator()(const f32x4 (&acc)[2][2][4][2], const Unit& u, int wr, int wc, int fr, int fq) const {
;     ...
;                 if (sl != 0 && sl != 63) *(u32x4*)(G + row * 5504 + jg0) = (u32x4){gq[0], gq[1], gq[2], gq[3]};
	v_or_b32_e32 v216, s39, v188
	v_mov_b64_e32 v[214:215], s[14:15]
	v_mad_u64_u32 v[214:215], s[48:49], v216, s71, v[214:215]
	v_mad_i32_i24 v215, s37, v250, v215
	v_lshl_add_u64 v[214:215], v[212:213], 1, v[214:215]
	global_store_dwordx4 v[214:215], v[176:179], off

; __global__ void __launch_bounds__(NTHREADS, 2) fwd(Args args) {
;     extern __shared__ __attribute__((aligned(16))) unsigned char lds_raw[];
	.amdhsa_kernel _Z3fwd4Args
		.amdhsa_group_segment_fixed_size 0
		.amdhsa_private_segment_fixed_size 0
		.amdhsa_kernarg_size 488
		.amdhsa_user_sgpr_count 2
		.amdhsa_user_sgpr_dispatch_ptr 0
		.amdhsa_user_sgpr_queue_ptr 0
		.amdhsa_user_sgpr_kernarg_segment_ptr 1
		.amdhsa_user_sgpr_dispatch_id 0
		.amdhsa_user_sgpr_kernarg_preload_length 0
		.amdhsa_user_sgpr_kernarg_preload_offset 0
		.amdhsa_user_sgpr_private_segment_size 0
		.amdhsa_uses_dynamic_stack 0
		.amdhsa_enable_private_segment 0
		.amdhsa_system_sgpr_workgroup_id_x 1
		.amdhsa_system_sgpr_workgroup_id_y 0
		.amdhsa_system_sgpr_workgroup_id_z 0
		.amdhsa_system_sgpr_workgroup_info 0
		.amdhsa_system_vgpr_workitem_id 0
		.amdhsa_next_free_vgpr 256
		.amdhsa_next_free_sgpr 100
		.amdhsa_accum_offset 256
		.amdhsa_reserve_vcc 1
		.amdhsa_float_round_mode_32 0
		.amdhsa_float_round_mode_16_64 0
		.amdhsa_float_denorm_mode_32 3
		.amdhsa_float_denorm_mode_16_64 3
		.amdhsa_dx10_clamp 1
		.amdhsa_ieee_mode 1
		.amdhsa_fp16_overflow 0
		.amdhsa_tg_split 0
		.amdhsa_exception_fp_ieee_invalid_op 0
		.amdhsa_exception_fp_denorm_src 0
		.amdhsa_exception_fp_ieee_div_zero 0
		.amdhsa_exception_fp_ieee_overflow 0
		.amdhsa_exception_fp_ieee_underflow 0
		.amdhsa_exception_fp_ieee_inexact 0
		.amdhsa_exception_int_div_zero 0
	.end_amdhsa_kernel

; __global__ void __launch_bounds__(NTHREADS, 2) fwd(Args args) {
;     extern __shared__ __attribute__((aligned(16))) unsigned char lds_raw[];
amdhsa.kernels:
  - .agpr_count:     0
    .args:
      - .offset:         0
        .size:           232
        .value_kind:     by_value
      - .offset:         232
        .size:           4
        .value_kind:     hidden_block_count_x
      - .offset:         236
        .size:           4
        .value_kind:     hidden_block_count_y
      - .offset:         240
        .size:           4
        .value_kind:     hidden_block_count_z
      - .offset:         244
        .size:           2
        .value_kind:     hidden_group_size_x
      - .offset:         246
        .size:           2
        .value_kind:     hidden_group_size_y
      - .offset:         248
        .size:           2
        .value_kind:     hidden_group_size_z
      - .offset:         250
        .size:           2
        .value_kind:     hidden_remainder_x
      - .offset:         252
        .size:           2
        .value_kind:     hidden_remainder_y
      - .offset:         254
        .size:           2
        .value_kind:     hidden_remainder_z
      - .offset:         272
        .size:           8
        .value_kind:     hidden_global_offset_x
      - .offset:         280
        .size:           8
        .value_kind:     hidden_global_offset_y
      - .offset:         288
        .size:           8
        .value_kind:     hidden_global_offset_z
      - .offset:         296
        .size:           2
        .value_kind:     hidden_grid_dims
      - .offset:         352
        .size:           4
        .value_kind:     hidden_dynamic_lds_size
    .group_segment_fixed_size: 0
    .kernarg_segment_align: 8
    .kernarg_segment_size: 488
    .language:       OpenCL C
    .language_version:
      - 2
      - 0
    .max_flat_workgroup_size: 512
    .name:           _Z3fwd4Args
    .private_segment_fixed_size: 0
    .sgpr_count:     106
    .sgpr_spill_count: 149
    .symbol:         _Z3fwd4Args.kd
    .uniform_work_group_size: 1
    .uses_dynamic_stack: false
    .vgpr_count:     256
    .vgpr_spill_count: 0
    .wavefront_size: 64
